# v19 + the compiler's vmcnt(0) flushes at the start of every attention block removed (the counted waits of the tile ring already retire the Q loads)
# baseline (speedup 1.0000x reference)
.LBB0_376:
	s_cmpk_gt_i32 s78, 0x5ff
	s_mov_b64 s[0:1], -1
	s_cbranch_scc0 .LBB0_398
	s_add_i32 s0, s78, 0xfffffa00
	s_lshr_b32 s1, s0, 6
	s_and_b32 s1, s1, 12
	s_add_i32 s1, s1, s78
	s_andn2_b32 s4, 15, s1
	s_lshl_b32 s46, s4, 3
	v_readlane_b32 s66, v254, 16
	s_lshr_b32 s69, s0, 8
	s_add_i32 s79, s46, s66
	s_lshl_b32 s0, s69, 12
	s_lshl_b32 s66, s79, 5
	s_add_i32 s66, s66, s0
	s_lshl_b32 s1, s78, 3
	v_or_b32_e32 v2, s66, v165
	s_and_b32 s1, s1, 0x780
	v_lshlrev_b64 v[4:5], 12, v[2:3]
	v_lshl_add_u64 v[4:5], s[48:49], 0, v[4:5]
	s_lshl_b32 s0, s1, 1
	s_mov_b32 s1, s77
	v_lshl_add_u64 v[4:5], v[4:5], 0, s[0:1]
	v_mov_b32_e32 v173, v3
	v_lshl_add_u64 v[4:5], v[4:5], 0, v[172:173]
	global_load_dwordx4 v[132:135], v[4:5], off
	global_load_dwordx4 v[136:139], v[4:5], off offset:32
	global_load_dwordx4 v[140:143], v[4:5], off offset:64
	global_load_dwordx4 v[144:147], v[4:5], off offset:96
	global_load_dwordx4 v[148:151], v[4:5], off offset:128
	global_load_dwordx4 v[152:155], v[4:5], off offset:160
	global_load_dwordx4 v[156:159], v[4:5], off offset:192
	global_load_dwordx4 v[160:163], v[4:5], off offset:224
	s_mov_b64 s[86:87], exec
	v_readlane_b32 s66, v254, 39
	v_readlane_b32 s67, v254, 40
	s_and_b64 s[66:67], s[86:87], s[66:67]
	s_mov_b64 exec, s[66:67]
	ds_write_b32 v199, v3
	s_or_b64 exec, exec, s[86:87]
	s_lshl_b32 s1, s69, 24
	v_readlane_b32 s66, v254, 28
	v_readlane_b32 s67, v254, 29
	s_add_u32 s69, s66, s1
	s_addc_u32 s76, s67, 0
	s_add_u32 s1, s50, s1
	s_addc_u32 s67, s51, 0
	s_add_u32 s66, s1, s0
	s_addc_u32 s67, s67, 0
	s_add_u32 s86, s69, s0
	s_addc_u32 s87, s76, 0
	s_lshl_b32 s1, s46, 17
	v_lshl_add_u64 v[4:5], s[66:67], 0, v[168:169]
	v_lshlrev_b32_e32 v6, 1, v164
	v_mov_b32_e32 v7, v3
	v_lshl_add_u64 v[174:175], v[4:5], 0, v[6:7]
	v_lshl_add_u64 v[4:5], s[86:87], 0, v[168:169]
	s_or_b32 s76, s1, 0xe0000
	s_mov_b32 m0, s94
	v_lshl_add_u64 v[176:177], v[4:5], 0, v[6:7]
	v_lshl_add_u64 v[4:5], v[174:175], 0, s[76:77]
	s_lshl_b32 s4, s4, 20
	global_load_lds_dwordx4 v[4:5], off
	v_lshl_add_u64 v[4:5], v[176:177], 0, s[76:77]
	s_mov_b32 m0, s56
	s_or_b32 s76, s4, 0xc0000
	global_load_lds_dwordx4 v[4:5], off
	v_lshl_add_u64 v[4:5], v[174:175], 0, s[76:77]
	s_mov_b32 m0, s57
	v_readlane_b32 s66, v254, 0
	global_load_lds_dwordx4 v[4:5], off
	v_lshl_add_u64 v[4:5], v[176:177], 0, s[76:77]
	s_mov_b32 m0, s89
	s_or_b32 s76, s4, 0xa0000
	global_load_lds_dwordx4 v[4:5], off
	v_lshl_add_u64 v[4:5], v[174:175], 0, s[76:77]
	s_mov_b32 m0, s93
	v_readlane_b32 s67, v254, 1
	global_load_lds_dwordx4 v[4:5], off
	v_lshl_add_u64 v[4:5], v[176:177], 0, s[76:77]
	s_mov_b32 m0, s68
	s_add_i32 s76, s1, 0x80000
	global_load_lds_dwordx4 v[4:5], off
	s_waitcnt vmcnt(4)
	v_readlane_b32 s1, v254, 42
	s_waitcnt lgkmcnt(0)
	s_barrier
	v_lshl_add_u64 v[4:5], v[174:175], 0, s[76:77]
	s_mov_b32 m0, s1
	v_readlane_b32 s1, v254, 43
	global_load_lds_dwordx4 v[4:5], off
	v_lshl_add_u64 v[4:5], v[176:177], 0, s[76:77]
	s_mov_b32 m0, s1
	s_andn2_b64 vcc, exec, s[66:67]
	global_load_lds_dwordx4 v[4:5], off
	s_cbranch_vccnz .LBB0_383
	v_add_u32_e32 v1, v197, v183
	ds_read_b128 v[4:7], v1
	v_add_u32_e32 v1, v197, v184
	ds_read_b128 v[20:23], v1
	v_add_u32_e32 v1, v197, v185
	s_andn2_b64 vcc, exec, s[82:83]
	s_waitcnt lgkmcnt(0)
	v_mfma_f32_32x32x16_bf16 v[4:19], v[4:7], v[132:135], 0
	v_mfma_f32_32x32x16_bf16 v[4:19], v[20:23], v[136:139], v[4:19]
	ds_read_b128 v[20:23], v1
	v_add_u32_e32 v1, v197, v186
	ds_read_b128 v[24:27], v1
	v_add_u32_e32 v1, v197, v187
	s_waitcnt lgkmcnt(1)
	v_mfma_f32_32x32x16_bf16 v[4:19], v[20:23], v[140:143], v[4:19]
	ds_read_b128 v[20:23], v1
	v_add_u32_e32 v1, v197, v188
	s_waitcnt lgkmcnt(1)
	v_mfma_f32_32x32x16_bf16 v[4:19], v[24:27], v[144:147], v[4:19]
	ds_read_b128 v[24:27], v1
	v_add_u32_e32 v1, v197, v189
	s_waitcnt lgkmcnt(1)
	v_mfma_f32_32x32x16_bf16 v[4:19], v[20:23], v[148:151], v[4:19]
	ds_read_b128 v[20:23], v1
	v_add_u32_e32 v1, v197, v190
	s_waitcnt lgkmcnt(1)
	v_mfma_f32_32x32x16_bf16 v[4:19], v[24:27], v[152:155], v[4:19]
	ds_read_b128 v[24:27], v1
	s_waitcnt lgkmcnt(1)
	v_mfma_f32_32x32x16_bf16 v[4:19], v[20:23], v[156:159], v[4:19]
	s_waitcnt lgkmcnt(0)
	v_mfma_f32_32x32x16_bf16 v[4:19], v[24:27], v[160:163], v[4:19]
	s_nop 11
	v_exp_f32_e64 v1, -|v4|
	v_exp_f32_e64 v21, -|v5|
	v_exp_f32_e64 v23, -|v6|
	v_exp_f32_e64 v27, -|v8|
	v_exp_f32_e64 v25, -|v7|
	v_exp_f32_e64 v29, -|v9|
	v_add_f32_e32 v1, 1.0, v1
	v_exp_f32_e64 v31, -|v10|
	v_add_f32_e32 v21, 1.0, v21
	v_add_f32_e32 v23, 1.0, v23
	v_add_f32_e32 v27, 1.0, v27
	v_log_f32_e32 v1, v1
	v_log_f32_e32 v21, v21
	v_log_f32_e32 v23, v23
	v_log_f32_e32 v27, v27
	v_exp_f32_e64 v33, -|v11|
	v_add_f32_e32 v25, 1.0, v25
	v_add_f32_e32 v29, 1.0, v29
	v_max_f32_e32 v20, 0, v4
	v_log_f32_e32 v25, v25
	v_log_f32_e32 v29, v29
	v_max_f32_e32 v22, 0, v5
	v_max_f32_e32 v24, 0, v6
	v_max_f32_e32 v28, 0, v8
	v_add_f32_e32 v31, 1.0, v31
	v_add_f32_e32 v1, v20, v1
	v_log_f32_e32 v31, v31
	v_add_f32_e32 v20, v22, v21
	v_add_f32_e32 v21, v24, v23
	v_add_f32_e32 v23, v28, v27
	v_cndmask_b32_e64 v27, 0, -v1, s[10:11]
	v_max_f32_e32 v26, 0, v7
	v_max_f32_e32 v30, 0, v9
	v_add_f32_e32 v33, 1.0, v33
	v_cndmask_b32_e64 v28, 0, -v20, s[12:13]
	v_cndmask_b32_e64 v27, -v1, v27, s[82:83]
	v_log_f32_e32 v33, v33
	v_add_f32_e32 v22, v26, v25
	v_add_f32_e32 v24, v30, v29
	v_cndmask_b32_e64 v29, 0, -v21, s[14:15]
	v_cndmask_b32_e64 v28, -v20, v28, s[82:83]
	v_add_f32_e32 v1, 0, v27
	v_max_f32_e32 v32, 0, v10
	v_cndmask_b32_e64 v30, 0, -v22, s[16:17]
	v_cndmask_b32_e64 v29, -v21, v29, s[82:83]
	v_add_f32_e32 v1, v28, v1
	v_exp_f32_e64 v35, -|v12|
	v_add_f32_e32 v25, v32, v31
	v_cndmask_b32_e64 v31, 0, -v23, s[18:19]
	v_cndmask_b32_e64 v30, -v22, v30, s[82:83]
	v_add_f32_e32 v1, v29, v1
	v_max_f32_e32 v34, 0, v11
	v_cndmask_b32_e64 v32, 0, -v24, s[20:21]
	v_cndmask_b32_e64 v31, -v23, v31, s[82:83]
	v_add_f32_e32 v1, v30, v1
	v_add_f32_e32 v26, v34, v33
	v_cndmask_b32_e64 v32, -v24, v32, s[82:83]
	v_add_f32_e32 v1, v31, v1
	v_add_f32_e32 v22, v32, v1
	v_cndmask_b32_e64 v1, 0, -v26, s[24:25]
	v_cndmask_b32_e64 v26, -v26, v1, s[82:83]
	v_add_f32_e32 v1, 1.0, v35
	v_log_f32_e32 v1, v1
	v_exp_f32_e64 v21, -|v13|
	v_max_f32_e32 v20, 0, v12
	v_add_f32_e32 v1, v20, v1
	v_cndmask_b32_e64 v20, 0, -v1, s[26:27]
	v_cndmask_b32_e64 v23, -v1, v20, s[82:83]
	v_add_f32_e32 v1, 1.0, v21
	v_log_f32_e32 v1, v1
	v_max_f32_e32 v21, 0, v13
	v_add_f32_e32 v20, 0, v23
	v_add_f32_e32 v1, v21, v1
	v_exp_f32_e64 v21, -|v14|
	v_cndmask_b32_e64 v24, 0, -v1, s[28:29]
	v_cndmask_b32_e64 v24, -v1, v24, s[82:83]
	v_add_f32_e32 v1, v24, v20
	v_add_f32_e32 v20, 1.0, v21
	v_log_f32_e32 v20, v20
	v_exp_f32_e64 v34, -|v15|
	v_max_f32_e32 v21, 0, v14
	v_add_f32_e32 v20, v21, v20
	v_cndmask_b32_e64 v21, 0, -v20, s[30:31]
	v_cndmask_b32_e64 v35, -v20, v21, s[82:83]
	v_add_f32_e32 v20, 1.0, v34
	v_log_f32_e32 v20, v20
	v_max_f32_e32 v21, 0, v15
	v_exp_f32_e64 v36, -|v17|
	v_add_f32_e32 v20, v21, v20
	v_exp_f32_e64 v21, -|v16|
	v_cndmask_b32_e64 v34, 0, -v20, s[34:35]
	v_cndmask_b32_e64 v34, -v20, v34, s[82:83]
	v_exp_f32_e64 v38, -|v19|
	v_add_f32_e32 v20, 1.0, v21
	v_log_f32_e32 v20, v20
	v_max_f32_e32 v21, 0, v16
	v_add_f32_e32 v1, v35, v1
	v_add_f32_e32 v20, v21, v20
	v_cndmask_b32_e64 v21, 0, -v20, s[36:37]
	v_cndmask_b32_e64 v37, -v20, v21, s[82:83]
	v_add_f32_e32 v20, 1.0, v36
	v_log_f32_e32 v20, v20
	v_max_f32_e32 v21, 0, v17
	v_add_f32_e32 v1, v34, v1
	v_add_f32_e32 v20, v21, v20
	v_exp_f32_e64 v21, -|v18|
	v_cndmask_b32_e64 v36, 0, -v20, s[38:39]
	v_cndmask_b32_e64 v36, -v20, v36, s[82:83]
	v_add_f32_e32 v1, v37, v1
	v_add_f32_e32 v20, 1.0, v21
	v_log_f32_e32 v20, v20
	v_max_f32_e32 v21, 0, v18
	v_add_f32_e32 v1, v36, v1
	v_add_f32_e32 v20, v21, v20
	v_cndmask_b32_e64 v21, 0, -v20, s[40:41]
	v_cndmask_b32_e64 v39, -v20, v21, s[82:83]
	v_add_f32_e32 v20, 1.0, v38
	v_log_f32_e32 v20, v20
	v_max_f32_e32 v21, 0, v19
	v_add_f32_e32 v1, v39, v1
	v_add_f32_e32 v20, v21, v20
	v_cndmask_b32_e64 v21, 0, -v20, s[42:43]
	v_cndmask_b32_e64 v38, -v20, v21, s[82:83]
	v_add_f32_e32 v20, v38, v1
	v_mov_b32_e32 v1, v20
	v_mov_b32_e32 v21, v20
	s_nop 1
	v_permlane32_swap_b32_e32 v1, v21
	v_cndmask_b32_e64 v21, v1, v21, s[2:3]
	v_add_f32_e32 v1, 0, v21
	v_cndmask_b32_e64 v40, 0, v1, s[6:7]
	v_add_f32_e32 v42, v1, v20
	v_add_f32_e32 v1, v19, v38
	v_add_f32_e32 v19, v40, v38
	v_add_f32_e32 v18, v18, v39
	v_add_f32_e32 v18, v19, v18
	v_add_f32_e32 v19, v39, v19
	v_add_f32_e32 v17, v17, v36
	v_add_f32_e32 v17, v17, v19
	v_add_f32_e32 v19, v36, v19
	v_add_f32_e32 v16, v16, v37
	v_add_f32_e32 v16, v16, v19
	v_add_f32_e32 v19, v37, v19
	v_add_f32_e32 v15, v15, v34
	v_add_f32_e32 v15, v15, v19
	v_add_f32_e32 v19, v34, v19
	v_add_f32_e32 v14, v14, v35
	v_cndmask_b32_e64 v33, 0, -v25, s[22:23]
	v_add_f32_e32 v14, v14, v19
	v_add_f32_e32 v19, v35, v19
	v_add_f32_e32 v13, v13, v24
	v_add_f32_e32 v13, v13, v19
	v_add_f32_e32 v19, v24, v19
	v_cndmask_b32_e64 v24, -v25, v33, s[82:83]
	v_add_f32_e32 v22, v24, v22
	v_add_f32_e32 v22, v26, v22
	v_add_f32_e32 v12, v12, v23
	v_mov_b32_e32 v23, v22
	v_mov_b32_e32 v25, v22
	s_nop 1
	v_permlane32_swap_b32_e32 v23, v25
	v_add_f32_e32 v41, 0, v20
	v_cndmask_b32_e64 v23, v23, v25, s[2:3]
	v_add_f32_e32 v12, v12, v19
	v_add_f32_e32 v19, v41, v21
	v_add_f32_e32 v25, v42, v23
	v_add_f32_e32 v11, v11, v26
	v_cndmask_b32_e64 v25, v19, v25, s[6:7]
	v_add_f32_e32 v11, v11, v25
	v_exp_f32_e32 v19, v11
	v_mov_b32_e32 v11, v26
	v_pk_add_f32 v[10:11], v[10:11], v[24:25]
	v_add_f32_e32 v9, v9, v32
	v_add_f32_e32 v10, v10, v11
	v_add_f32_e32 v11, v24, v11
	v_add_f32_e32 v9, v9, v11
	v_add_f32_e32 v11, v32, v11
	v_add_f32_e32 v8, v8, v31
	v_add_f32_e32 v8, v8, v11
	v_add_f32_e32 v11, v31, v11
	v_add_f32_e32 v7, v7, v30
	v_add_f32_e32 v7, v7, v11
	v_add_f32_e32 v11, v30, v11
	v_add_f32_e32 v6, v6, v29
	v_add_f32_e32 v6, v6, v11
	v_add_f32_e32 v11, v29, v11
	v_add_f32_e32 v5, v5, v28
	v_add_f32_e32 v5, v5, v11
	v_add_f32_e32 v11, v28, v11
	v_add_f32_e32 v4, v4, v27
	v_add_f32_e32 v1, v40, v1
	v_add_f32_e32 v4, v4, v11
	v_exp_f32_e32 v1, v1
	v_exp_f32_e32 v18, v18
	v_exp_f32_e32 v17, v17
	v_exp_f32_e32 v16, v16
	v_exp_f32_e32 v15, v15
	v_exp_f32_e32 v14, v14
	v_exp_f32_e32 v13, v13
	v_exp_f32_e32 v12, v12
	v_exp_f32_e32 v10, v10
	v_exp_f32_e32 v9, v9
	v_exp_f32_e32 v8, v8
	v_exp_f32_e32 v7, v7
	v_exp_f32_e32 v6, v6
	v_exp_f32_e32 v5, v5
	v_exp_f32_e32 v4, v4
	s_cbranch_vccnz .LBB0_382
	s_or_b64 vcc, s[12:13], s[10:11]
	v_cndmask_b32_e32 v4, 0, v4, vcc
	s_or_b64 vcc, s[16:17], s[14:15]
	v_cndmask_b32_e32 v6, 0, v6, vcc
	s_or_b64 vcc, s[20:21], s[18:19]
	v_cndmask_b32_e32 v8, 0, v8, vcc
	s_or_b64 vcc, s[24:25], s[22:23]
	v_cndmask_b32_e32 v10, 0, v10, vcc
	s_or_b64 vcc, s[28:29], s[26:27]
	v_cndmask_b32_e32 v12, 0, v12, vcc
	s_or_b64 vcc, s[34:35], s[30:31]
	v_cndmask_b32_e32 v14, 0, v14, vcc
	s_or_b64 vcc, s[38:39], s[36:37]
	v_cndmask_b32_e32 v16, 0, v16, vcc
	s_or_b64 vcc, s[42:43], s[40:41]
	v_cndmask_b32_e64 v5, 0, v5, s[12:13]
	v_cndmask_b32_e64 v7, 0, v7, s[16:17]
	v_cndmask_b32_e64 v9, 0, v9, s[20:21]
	v_cndmask_b32_e64 v19, 0, v19, s[24:25]
	v_cndmask_b32_e64 v13, 0, v13, s[28:29]
	v_cndmask_b32_e64 v15, 0, v15, s[34:35]
	v_cndmask_b32_e64 v17, 0, v17, s[38:39]
	v_cndmask_b32_e64 v1, 0, v1, s[42:43]
	v_cndmask_b32_e32 v18, 0, v18, vcc

.LBB0_383:
	v_mov_b32_e32 v82, v3
	v_mov_b32_e32 v83, v3
	v_mov_b32_e32 v68, v3
	v_mov_b32_e32 v69, v3
	v_mov_b32_e32 v70, v3
	v_mov_b32_e32 v71, v3
	v_mov_b32_e32 v72, v3
	v_mov_b32_e32 v73, v3
	v_mov_b32_e32 v74, v3
	v_mov_b32_e32 v75, v3
	v_mov_b32_e32 v76, v3
	v_mov_b32_e32 v77, v3
	v_mov_b32_e32 v78, v3
	v_mov_b32_e32 v79, v3
	v_mov_b32_e32 v80, v3
	v_mov_b32_e32 v81, v3
	v_mov_b64_e32 v[98:99], v[82:83]
	v_mov_b64_e32 v[114:115], v[82:83]
	v_mov_b64_e32 v[130:131], v[82:83]
	s_mov_b64 s[86:87], 0
	v_mov_b32_e32 v173, 0
	v_mov_b64_e32 v[96:97], v[80:81]
	v_mov_b64_e32 v[94:95], v[78:79]
	v_mov_b64_e32 v[92:93], v[76:77]
	v_mov_b64_e32 v[90:91], v[74:75]
	v_mov_b64_e32 v[88:89], v[72:73]
	v_mov_b64_e32 v[86:87], v[70:71]
	v_mov_b64_e32 v[84:85], v[68:69]
	v_mov_b64_e32 v[112:113], v[80:81]
	v_mov_b64_e32 v[110:111], v[78:79]
	v_mov_b64_e32 v[108:109], v[76:77]
	v_mov_b64_e32 v[106:107], v[74:75]
	v_mov_b64_e32 v[104:105], v[72:73]
	v_mov_b64_e32 v[102:103], v[70:71]
	v_mov_b64_e32 v[100:101], v[68:69]
	v_mov_b64_e32 v[128:129], v[80:81]
	v_mov_b64_e32 v[126:127], v[78:79]
	v_mov_b64_e32 v[124:125], v[76:77]
	v_mov_b64_e32 v[122:123], v[74:75]
	v_mov_b64_e32 v[120:121], v[72:73]
	v_mov_b64_e32 v[118:119], v[70:71]
	v_mov_b64_e32 v[116:117], v[68:69]
	v_lshlrev_b64 v[178:179], 11, v[2:3]
	s_and_saveexec_b64 s[90:91], s[8:9]

.LBB0_385:
	s_or_b64 exec, exec, s[90:91]
	s_lshr_b32 s1, s88, 6
	s_and_b32 s1, s1, 0x3fffffc
	s_sub_i32 s1, s95, s1
	s_and_b32 s1, s1, 15
	s_lshl_b32 s1, s1, 3
	s_or_b32 s1, s1, 6
	s_mov_b32 s4, 0x10000
	s_mov_b32 s69, 8
	v_readlane_b32 s76, v254, 41
	v_mov_b64_e32 v[4:5], v[116:117]
	v_mov_b64_e32 v[6:7], v[118:119]
	v_mov_b64_e32 v[8:9], v[120:121]
	v_mov_b64_e32 v[10:11], v[122:123]
	v_mov_b64_e32 v[12:13], v[124:125]
	v_mov_b64_e32 v[14:15], v[126:127]
	v_mov_b64_e32 v[16:17], v[128:129]
	v_mov_b64_e32 v[18:19], v[130:131]
	v_mov_b64_e32 v[20:21], v[100:101]
	v_mov_b64_e32 v[22:23], v[102:103]
	v_mov_b64_e32 v[24:25], v[104:105]
	v_mov_b64_e32 v[26:27], v[106:107]
	v_mov_b64_e32 v[28:29], v[108:109]
	v_mov_b64_e32 v[30:31], v[110:111]
	v_mov_b64_e32 v[32:33], v[112:113]
	v_mov_b64_e32 v[34:35], v[114:115]
	v_mov_b64_e32 v[36:37], v[68:69]
	v_mov_b64_e32 v[38:39], v[70:71]
	v_mov_b64_e32 v[40:41], v[72:73]
	v_mov_b64_e32 v[42:43], v[74:75]
	v_mov_b64_e32 v[44:45], v[76:77]
	v_mov_b64_e32 v[46:47], v[78:79]
	v_mov_b64_e32 v[48:49], v[80:81]
	v_mov_b64_e32 v[50:51], v[82:83]
	v_mov_b64_e32 v[52:53], v[84:85]
	v_mov_b64_e32 v[54:55], v[86:87]
	v_mov_b64_e32 v[56:57], v[88:89]
	v_mov_b64_e32 v[58:59], v[90:91]
	v_mov_b64_e32 v[60:61], v[92:93]
	v_mov_b64_e32 v[62:63], v[94:95]
	v_mov_b64_e32 v[64:65], v[96:97]
	v_mov_b64_e32 v[66:67], v[98:99]
	s_branch .LBB0_388

.LBB0_398:
	s_and_b64 vcc, exec, s[0:1]
	s_cbranch_vccz .LBB0_375
	s_ashr_i32 s90, s78, 9
	s_lshl_b32 s0, s90, 1
	s_lshl_b32 s4, s78, 8
	s_lshr_b32 s1, 0x1000, s0
	s_and_b32 s4, s4, 0xf00
	s_sub_i32 s0, 12, s0
	s_lshr_b32 s0, s4, s0
	s_mul_i32 s1, s0, s1
	s_sub_i32 s0, s4, s1
	s_ashr_i32 s91, s90, 31
	s_lshl_b32 s4, s78, 5
	s_ashr_i32 s86, s0, 5
	v_readlane_b32 s0, v254, 16
	s_lshl_b64 s[90:91], s[90:91], 14
	s_and_b32 s4, s4, 0x3000
	s_bfe_u32 s79, s78, 0x30004
	s_add_i32 s87, s86, s0
	s_max_i32 s0, s86, 4
	s_or_b32 s4, s90, s4
	s_add_u32 s90, s4, s1
	s_addc_u32 s91, s91, 0
	v_lshl_or_b32 v132, s87, 5, v165
	s_lshl_b64 vcc, s[90:91], 11
	v_readlane_b32 s1, v254, 30
	v_ashrrev_i32_e32 v133, 31, v132
	s_add_u32 s1, s1, vcc_lo
	v_readlane_b32 s4, v254, 31
	v_lshl_add_u64 v[130:131], s[90:91], 0, v[132:133]
	s_addc_u32 s4, s4, vcc_hi
	s_lshl_b32 s76, s79, 8
	s_add_i32 s46, s86, 7
	s_add_i32 s90, s0, -4
	v_readlane_b32 s66, v254, 35
	s_add_u32 s66, s66, vcc_lo
	v_readlane_b32 s67, v254, 34
	s_addc_u32 s67, s67, vcc_hi
	v_lshlrev_b64 v[4:5], 11, v[130:131]
	s_add_u32 vcc_lo, s66, s76
	v_lshl_add_u64 v[4:5], s[70:71], 0, v[4:5]
	s_addc_u32 vcc_hi, s67, 0
	v_lshl_add_u64 v[4:5], v[4:5], 0, s[76:77]
	v_mov_b32_e32 v173, v3
	s_add_u32 s66, s1, s76
	v_lshl_add_u64 v[4:5], v[4:5], 0, v[172:173]
	s_addc_u32 s67, s4, 0
	s_max_i32 s1, s46, s90
	global_load_dwordx4 v[98:101], v[4:5], off
	global_load_dwordx4 v[102:105], v[4:5], off offset:32
	global_load_dwordx4 v[106:109], v[4:5], off offset:64
	global_load_dwordx4 v[110:113], v[4:5], off offset:96
	global_load_dwordx4 v[114:117], v[4:5], off offset:128
	global_load_dwordx4 v[118:121], v[4:5], off offset:160
	global_load_dwordx4 v[122:125], v[4:5], off offset:192
	global_load_dwordx4 v[126:129], v[4:5], off offset:224
	v_lshl_add_u64 v[4:5], vcc, 0, v[170:171]
	v_lshlrev_b32_e32 v2, 1, v164
	s_lshl_b32 s76, s1, 5
	s_add_i32 s1, s86, 6
	v_lshl_add_u64 v[134:135], v[4:5], 0, v[2:3]
	v_lshl_add_u64 v[4:5], s[66:67], 0, v[170:171]
	s_lshl_b64 s[66:67], s[76:77], 11
	s_max_i32 s1, s1, s90
	s_mov_b32 m0, s94
	v_lshl_add_u64 v[136:137], v[4:5], 0, v[2:3]
	v_lshl_add_u64 v[4:5], v[134:135], 0, s[66:67]
	s_lshl_b32 s76, s1, 5
	s_add_i32 s1, s86, 5
	global_load_lds_dwordx4 v[4:5], off
	v_lshl_add_u64 v[4:5], v[136:137], 0, s[66:67]
	s_mov_b32 m0, s56
	s_lshl_b64 s[66:67], s[76:77], 11
	s_max_i32 s1, s1, s90
	global_load_lds_dwordx4 v[4:5], off
	v_lshl_add_u64 v[4:5], v[134:135], 0, s[66:67]
	s_mov_b32 m0, s57
	s_lshl_b32 s76, s1, 5
	global_load_lds_dwordx4 v[4:5], off
	v_lshl_add_u64 v[4:5], v[136:137], 0, s[66:67]
	s_mov_b32 m0, s89
	s_lshl_b64 s[66:67], s[76:77], 11
	global_load_lds_dwordx4 v[4:5], off
	v_lshl_add_u64 v[4:5], v[134:135], 0, s[66:67]
	s_mov_b32 m0, s93
	s_cmp_lt_i32 s46, s90
	global_load_lds_dwordx4 v[4:5], off
	v_lshl_add_u64 v[4:5], v[136:137], 0, s[66:67]
	s_mov_b32 m0, s68
	s_nop 0
	global_load_lds_dwordx4 v[4:5], off
	s_cbranch_scc1 .LBB0_411
	v_mov_b32_e32 v16, v3
	v_mov_b32_e32 v17, v3
	s_sub_i32 s91, s0, s86
	v_mov_b32_e32 v2, v3
	v_mov_b32_e32 v4, v3
	v_mov_b32_e32 v5, v3
	v_mov_b32_e32 v6, v3
	v_mov_b32_e32 v7, v3
	v_mov_b32_e32 v8, v3
	v_mov_b32_e32 v9, v3
	v_mov_b32_e32 v10, v3
	v_mov_b32_e32 v11, v3
	v_mov_b32_e32 v12, v3
	v_mov_b32_e32 v13, v3
	v_mov_b32_e32 v14, v3
	v_mov_b32_e32 v15, v3
	v_mov_b64_e32 v[32:33], v[16:17]
	v_mov_b64_e32 v[48:49], v[16:17]
	v_mov_b64_e32 v[64:65], v[16:17]
	v_mov_b64_e32 v[80:81], v[16:17]
	s_add_i32 s91, s91, -12
	v_lshl_add_u32 v1, s86, 5, v198
	s_mov_b32 s69, 0
	v_mov_b32_e32 v133, 0
	v_mov_b32_e32 v138, 0xf149f2ca
	s_mov_b32 s4, 0
	v_mov_b64_e32 v[30:31], v[14:15]
	v_mov_b64_e32 v[28:29], v[12:13]
	v_mov_b64_e32 v[26:27], v[10:11]
	v_mov_b64_e32 v[24:25], v[8:9]
	v_mov_b64_e32 v[22:23], v[6:7]
	v_mov_b64_e32 v[20:21], v[4:5]
	v_mov_b64_e32 v[18:19], v[2:3]
	v_mov_b64_e32 v[46:47], v[14:15]
	v_mov_b64_e32 v[44:45], v[12:13]
	v_mov_b64_e32 v[42:43], v[10:11]
	v_mov_b64_e32 v[40:41], v[8:9]
	v_mov_b64_e32 v[38:39], v[6:7]
	v_mov_b64_e32 v[36:37], v[4:5]
	v_mov_b64_e32 v[34:35], v[2:3]
	v_mov_b64_e32 v[62:63], v[14:15]
	v_mov_b64_e32 v[60:61], v[12:13]
	v_mov_b64_e32 v[58:59], v[10:11]
	v_mov_b64_e32 v[56:57], v[8:9]
	v_mov_b64_e32 v[54:55], v[6:7]
	v_mov_b64_e32 v[52:53], v[4:5]
	v_mov_b64_e32 v[50:51], v[2:3]
	v_mov_b64_e32 v[78:79], v[14:15]
	v_mov_b64_e32 v[76:77], v[12:13]
	v_mov_b64_e32 v[74:75], v[10:11]
	v_mov_b64_e32 v[72:73], v[8:9]
	v_mov_b64_e32 v[70:71], v[6:7]
	v_mov_b64_e32 v[68:69], v[4:5]
	v_mov_b64_e32 v[66:67], v[2:3]
	s_branch .LBB0_403
